# moba_kv tile loop: list entry fetched one more tile ahead (no per-tile vmcnt(0) round trip / store drain at the loop head)
# speedup vs baseline: 1.0028x; 1.0008x over previous
; #define LAS __attribute__((address_space(3)))
; __device__ __forceinline__ void moba_kv_item(LAS unsigned char* lds, const Ptrs& P, int bh, int n, int part, bool split) {
;     ...
;     const int b = bh >> 3, h = bh & 7;
;     const float SC = 0.08838834764831845f * LOG2E;
;     LAS unsigned char* kb = lds; LAS unsigned char* vb = lds + 69632; LAS float* lut = (LAS float*)(lds + 136192);
;     if (tid < 129) lut[tid] = P.rpe[t5_bucket(tid) * 24 + h] * LOG2E;
;     const float cbias = P.rpe[31 * 24 + h] * LOG2E;
;     {   const int kr = tid >> 4, kc8 = tid & 15, vd = tid >> 5, vk8 = tid & 31;
;         u32x4 rg[8], rv[8];
; #pragma unroll
;         for (int i = 0; i < 8; ++i) rg[i] = *(const u32x4*)(P.PA() + (size_t)(b * SEQ + n * 256 + kr + 32 * i) * NA + C_KA + h * 128 + kc8 * 8);
; #pragma unroll
;         for (int i = 0; i < 8; ++i) rv[i] = *(const u32x4*)(P.VTA() + ((size_t)(bh * 128 + vd + 16 * i)) * SEQ + n * 256 + vk8 * 8);
; #pragma unroll
;         for (int i = 0; i < 8; ++i) *(LAS u32x4*)(kb + (kr + 32 * i) * 272 + kc8 * 16) = rg[i];
; #pragma unroll
;         for (int i = 0; i < 8; ++i) { *(LAS u32x2*)(vb + (vd + 16 * i) * 520 + vk8 * 16) = (u32x2){rv[i].x, rv[i].y}; *(LAS u32x2*)(vb + (vd + 16 * i) * 520 + vk8 * 16 + 8) = (u32x2){rv[i].z, rv[i].w}; }
;     }
;     int cnt = (int)P.SELCNT()[bh * 16 + n]; cnt = cnt < 4096 ? cnt : 4096; cnt = __builtin_amdgcn_readfirstlane(cnt);
;     int beg = 0, end = cnt;
;     if (split) { int half = ((cnt >> 1) + 31) & ~31; half = half < cnt ? half : cnt; if (part == 0) end = half; else beg = half; }
;     __syncthreads();
.LBB0_938:
	s_or_b64 exec, exec, s[0:1]
	s_and_b32 s2, 0xffff, s4
	s_and_b32 s3, s2, 15
	s_lshl_b32 s78, s3, 8
	v_ashrrev_i32_e32 v72, 4, v1
	s_or_b32 s0, s78, s70
	v_add_u32_e32 v3, s0, v72
	v_mov_b64_e32 v[28:29], s[12:13]
	v_mad_i64_i32 v[4:5], s[0:1], v3, s57, v[28:29]
	v_lshlrev_b32_e32 v6, 4, v1
	v_lshl_add_u64 v[4:5], v[4:5], 0, s[8:9]
	v_and_b32_e32 v68, 0xf0, v6
	v_mov_b32_e32 v69, v0
	v_add_u32_e32 v6, 32, v3
	v_lshl_add_u64 v[4:5], v[4:5], 0, v[68:69]
	v_mad_i64_i32 v[6:7], s[0:1], v6, s57, v[28:29]
	v_add_co_u32_e32 v4, vcc, s58, v4
	v_lshl_add_u64 v[6:7], v[6:7], 0, s[8:9]
	v_add_u32_e32 v12, 64, v3
	v_addc_co_u32_e32 v5, vcc, 0, v5, vcc
	v_lshl_add_u64 v[6:7], v[6:7], 0, v[68:69]
	v_mad_i64_i32 v[12:13], s[0:1], v12, s57, v[28:29]
	v_add_co_u32_e32 v8, vcc, s58, v6
	v_lshl_add_u64 v[12:13], v[12:13], 0, s[8:9]
	v_add_u32_e32 v14, 0x60, v3
	v_addc_co_u32_e32 v9, vcc, 0, v7, vcc
	v_lshl_add_u64 v[12:13], v[12:13], 0, v[68:69]
	v_mad_i64_i32 v[14:15], s[0:1], v14, s57, v[28:29]
	v_add_co_u32_e32 v12, vcc, s58, v12
	v_lshl_add_u64 v[14:15], v[14:15], 0, s[8:9]
	v_add_u32_e32 v20, 0x80, v3
	v_addc_co_u32_e32 v13, vcc, 0, v13, vcc
	v_lshl_add_u64 v[14:15], v[14:15], 0, v[68:69]
	v_mad_i64_i32 v[20:21], s[0:1], v20, s57, v[28:29]
	v_add_co_u32_e32 v16, vcc, s58, v14
	v_lshl_add_u64 v[20:21], v[20:21], 0, s[8:9]
	v_add_u32_e32 v22, 0xa0, v3
	v_addc_co_u32_e32 v17, vcc, 0, v15, vcc
	v_lshl_add_u64 v[20:21], v[20:21], 0, v[68:69]
	v_mad_i64_i32 v[22:23], s[0:1], v22, s57, v[28:29]
	v_add_co_u32_e32 v20, vcc, s58, v20
	v_lshl_add_u64 v[22:23], v[22:23], 0, s[8:9]
	v_add_u32_e32 v30, 0xc0, v3
	v_add_u32_e32 v3, 0xe0, v3
	v_addc_co_u32_e32 v21, vcc, 0, v21, vcc
	v_lshl_add_u64 v[22:23], v[22:23], 0, v[68:69]
	v_mad_i64_i32 v[30:31], s[0:1], v30, s57, v[28:29]
	v_mad_i64_i32 v[28:29], s[0:1], v3, s57, v[28:29]
	v_add_co_u32_e32 v24, vcc, s58, v22
	v_lshl_add_u64 v[30:31], v[30:31], 0, s[8:9]
	v_lshl_add_u64 v[28:29], v[28:29], 0, s[8:9]
	s_ashr_i32 s74, s5, 6
	v_addc_co_u32_e32 v25, vcc, 0, v23, vcc
	v_lshl_add_u64 v[30:31], v[30:31], 0, v[68:69]
	v_lshl_add_u64 v[28:29], v[28:29], 0, v[68:69]
	v_ashrrev_i32_e32 v69, 5, v1
	s_lshl_b32 s0, s3, 9
	v_and_b32_e32 v2, 31, v1
	v_add_co_u32_e32 v30, vcc, s58, v30
	v_add_u32_e32 v36, s71, v69
	s_add_u32 s0, s37, s0
	v_addc_co_u32_e32 v31, vcc, 0, v31, vcc
	s_addc_u32 s1, s38, 0
	v_lshlrev_b32_e32 v70, 4, v2
	v_mov_b32_e32 v71, v0
	v_ashrrev_i32_e32 v37, 31, v36
	v_add_co_u32_e32 v32, vcc, s58, v28
	v_lshl_add_u64 v[38:39], s[0:1], 0, v[70:71]
	v_lshlrev_b64 v[36:37], 13, v[36:37]
	v_addc_co_u32_e32 v33, vcc, 0, v29, vcc
	v_lshl_add_u64 v[60:61], v[38:39], 0, v[36:37]
	v_add_co_u32_e32 v40, vcc, s59, v60
	global_load_dwordx4 v[4:7], v[4:5], off offset:2048
	s_nop 0
	global_load_dwordx4 v[8:11], v[8:9], off offset:2048
	v_addc_co_u32_e32 v41, vcc, 0, v61, vcc
	v_add_co_u32_e32 v44, vcc, s60, v60
	global_load_dwordx4 v[12:15], v[12:13], off offset:2048
	s_nop 0
	global_load_dwordx4 v[16:19], v[16:17], off offset:2048
	v_addc_co_u32_e32 v45, vcc, 0, v61, vcc
	v_add_co_u32_e32 v48, vcc, s61, v60
	global_load_dwordx4 v[20:23], v[20:21], off offset:2048
	s_nop 0
	global_load_dwordx4 v[24:27], v[24:25], off offset:2048
	v_addc_co_u32_e32 v49, vcc, 0, v61, vcc
	global_load_dwordx4 v[28:31], v[30:31], off offset:2048
	s_nop 0
	global_load_dwordx4 v[32:35], v[32:33], off offset:2048
	v_add_co_u32_e32 v52, vcc, s62, v60
	global_load_dwordx4 v[36:39], v[60:61], off
	s_nop 0
	global_load_dwordx4 v[40:43], v[40:41], off
	v_addc_co_u32_e32 v53, vcc, 0, v61, vcc
	v_add_co_u32_e32 v56, vcc, s63, v60
	s_or_b32 s0, s3, s72
	s_nop 0
	v_addc_co_u32_e32 v57, vcc, 0, v61, vcc
	v_add_co_u32_e32 v62, vcc, s64, v60
	global_load_dwordx4 v[44:47], v[44:45], off
	s_nop 0
	global_load_dwordx4 v[48:51], v[48:49], off
	v_addc_co_u32_e32 v63, vcc, 0, v61, vcc
	s_ashr_i32 s1, s0, 31
	v_add_co_u32_e32 v64, vcc, s65, v60
	s_lshl_b64 s[4:5], s[0:1], 2
	global_load_dwordx4 v[52:55], v[52:53], off
	s_nop 0
	global_load_dwordx4 v[56:59], v[56:57], off
	v_addc_co_u32_e32 v65, vcc, 0, v61, vcc
	s_add_u32 s4, s39, s4
	global_load_dwordx4 v[60:63], v[62:63], off
	s_nop 0
	global_load_dwordx4 v[64:67], v[64:65], off
	s_addc_u32 s5, s40, s5
	global_load_dword v71, v0, s[4:5]
	global_load_dword v3, v0, s[28:29] offset:2976
	v_mul_lo_u32 v72, v72, s66
	v_add3_u32 v68, 0, v68, v72
	s_waitcnt vmcnt(17)
	ds_write_b128 v68, v[4:7]
	s_waitcnt vmcnt(16)
	ds_write_b128 v68, v[8:11] offset:8704
	s_waitcnt vmcnt(15)
	ds_write_b128 v68, v[12:15] offset:17408
	s_waitcnt vmcnt(14)
	ds_write_b128 v68, v[16:19] offset:26112
	s_waitcnt vmcnt(13)
	ds_write_b128 v68, v[20:23] offset:34816
	s_waitcnt vmcnt(12)
	ds_write_b128 v68, v[24:27] offset:43520
	s_waitcnt vmcnt(11)
	ds_write_b128 v68, v[28:31] offset:52224
	s_waitcnt vmcnt(10)
	ds_write_b128 v68, v[32:35] offset:60928
	v_mul_lo_u32 v4, v69, s68
	v_add3_u32 v4, s67, v70, v4
	v_add_u32_e32 v5, 0x2080, v4
	s_waitcnt vmcnt(8)
	ds_write2_b64 v5, v[40:41], v[42:43] offset1:1
	v_add_u32_e32 v5, 0x4100, v4
	ds_write2_b64 v4, v[36:37], v[38:39] offset1:1
	s_and_b32 s2, s2, 48
	s_waitcnt vmcnt(7)
	ds_write2_b64 v5, v[44:45], v[46:47] offset1:1
	v_add_u32_e32 v5, 0x6180, v4
	s_waitcnt vmcnt(6)
	ds_write2_b64 v5, v[48:49], v[50:51] offset1:1
	v_add_u32_e32 v5, 0x8200, v4
	s_waitcnt vmcnt(5)
	ds_write2_b64 v5, v[52:53], v[54:55] offset1:1
	v_add_u32_e32 v5, 0xa280, v4
	s_waitcnt vmcnt(4)
	ds_write2_b64 v5, v[56:57], v[58:59] offset1:1
	v_add_u32_e32 v5, 0xc300, v4
	v_add_u32_e32 v4, 0xe380, v4
	s_waitcnt vmcnt(2)
	ds_write2_b64 v4, v[64:65], v[66:67] offset1:1
	s_waitcnt vmcnt(1)
	v_min_i32_e32 v4, 0x1000, v71
	ds_write2_b64 v5, v[60:61], v[62:63] offset1:1
	v_readfirstlane_b32 s3, v4
	s_ashr_i32 s4, s3, 1
	s_add_i32 s4, s4, 31
	s_andn2_b32 s4, s4, 31
	s_min_i32 s4, s4, s3
	s_cmp_eq_u32 s2, 32
	s_cselect_b32 s75, s4, s3
	s_cmp_eq_u32 s2, 48
	s_cselect_b32 s76, s4, 0
	s_sub_i32 s2, s75, s76
	s_add_i32 s2, s2, 31
	s_ashr_i32 s77, s2, 5
	s_cmp_ge_i32 s74, s77
	s_waitcnt lgkmcnt(0)
	s_barrier
; __device__ __forceinline__ void moba_load_q(bf16x8 (&qr)[8], const Ptrs& P, size_t qrow, int h, int hi) {
; #pragma unroll
;     for (int ks = 0; ks < 8; ++ks) qr[ks] = *(const bf16x8*)(P.PA() + qrow * NA + C_QA + h * 128 + ks * 16 + hi * 8);
; }
; __device__ __forceinline__ void moba_kv_item(LAS unsigned char* lds, const Ptrs& P, int bh, int n, int part, bool split) {
;     ...
;     const int ntile = (end - beg + 31) >> 5;
;     const unsigned* list = P.LIST() + (size_t)(bh * 16 + n) * 4096;
;     bf16x8 qn[8]; unsigned en = 0u; bool vn = false;
;     if (wid < ntile) { const int idx = beg + wid * 32 + r32; vn = idx < end; en = list[vn ? idx : beg]; moba_load_q(qn, P, (size_t)(b * SEQ + (int)(en & 4095u)), h, hi); }
	s_cbranch_scc1 .LBB0_931
	v_lshl_or_b32 v4, s74, 5, v2
	v_add_u32_e32 v4, s76, v4
	s_lshl_b64 s[0:1], s[0:1], 14
	v_mov_b32_e32 v5, s76
	v_cmp_gt_i32_e64 s[46:47], s75, v4
	s_add_u32 s34, s41, s0
	s_addc_u32 s35, s42, s1
	v_cndmask_b32_e64 v4, v5, v4, s[46:47]
	v_ashrrev_i32_e32 v5, 31, v4
	v_lshl_add_u64 v[4:5], v[4:5], 2, s[34:35]
	global_load_dword v228, v[4:5], off
	v_bfe_u32 v1, v1, 5, 1
	v_mov_b64_e32 v[8:9], s[26:27]
	v_mov_b64_e32 v[4:5], s[30:31]
	v_mov_b32_e32 v7, v0
	v_lshlrev_b32_e32 v6, 4, v1
	s_waitcnt vmcnt(1)
	v_mul_f32_e32 v208, 0x3fb8aa3b, v3
	v_cmp_eq_u32_e64 s[2:3], 0, v1
	v_add_u32_e32 v223, s76, v2
	v_mov_b32_e32 v210, v208
	v_mov_b32_e32 v211, v208
	v_lshl_add_u64 v[212:213], s[30:31], 0, v[6:7]
	v_mad_u32_u24 v226, v2, s66, v6
	s_mov_b64 s[4:5], s[46:47]
	s_waitcnt vmcnt(0)
	v_and_b32_e32 v10, 0xfff, v228
	v_or_b32_e32 v10, s70, v10
	v_mad_i64_i32 v[8:9], s[0:1], v10, s57, v[8:9]
	v_mad_i64_i32 v[4:5], s[0:1], v10, s57, v[4:5]
	v_lshl_add_u64 v[8:9], v[8:9], 0, v[6:7]
	v_lshl_add_u64 v[4:5], v[4:5], 0, v[6:7]
	v_add_co_u32_e32 v8, vcc, s58, v8
	v_mov_b32_e32 v227, v228
	s_nop 0
	v_addc_co_u32_e32 v9, vcc, 0, v9, vcc
	global_load_dwordx4 v[176:179], v[4:5], off
	global_load_dwordx4 v[180:183], v[8:9], off offset:32
	global_load_dwordx4 v[184:187], v[8:9], off offset:64
	global_load_dwordx4 v[188:191], v[8:9], off offset:96
	global_load_dwordx4 v[192:195], v[8:9], off offset:128
	global_load_dwordx4 v[196:199], v[8:9], off offset:160
	global_load_dwordx4 v[200:203], v[8:9], off offset:192
	global_load_dwordx4 v[204:207], v[8:9], off offset:224
	v_mov_b32_e32 v5, v0
	v_lshlrev_b32_e32 v4, 3, v1
	v_lshl_add_u32 v1, v1, 2, s78
	s_addk_i32 s78, 0x17f
	v_lshl_add_u64 v[214:215], s[16:17], 0, v[4:5]
	v_mad_u32_u24 v224, v2, s68, v4
	v_sub_u32_e32 v225, 0, v1
	v_lshlrev_b32_e32 v216, 1, v4
	s_waitcnt vmcnt(7)
	v_mov_b64_e32 v[144:145], v[176:177]
	s_waitcnt vmcnt(6)
	v_mov_b64_e32 v[148:149], v[180:181]
	s_waitcnt vmcnt(5)
	v_mov_b64_e32 v[152:153], v[184:185]
	s_waitcnt vmcnt(4)
	v_mov_b64_e32 v[156:157], v[188:189]
	s_waitcnt vmcnt(3)
	v_mov_b64_e32 v[160:161], v[192:193]
	s_waitcnt vmcnt(2)
	v_mov_b64_e32 v[164:165], v[196:197]
	s_waitcnt vmcnt(1)
	v_mov_b64_e32 v[168:169], v[200:201]
	s_waitcnt vmcnt(0)
	v_mov_b64_e32 v[172:173], v[204:205]
	v_mov_b64_e32 v[146:147], v[178:179]
	v_mov_b64_e32 v[150:151], v[182:183]
	v_mov_b64_e32 v[154:155], v[186:187]
	v_mov_b64_e32 v[158:159], v[190:191]
	v_mov_b64_e32 v[162:163], v[194:195]
	v_mov_b64_e32 v[166:167], v[198:199]
	v_mov_b64_e32 v[170:171], v[202:203]
	v_mov_b64_e32 v[174:175], v[206:207]
	s_mov_b32 s93, 0
	s_branch .LBB0_942

; __device__ __forceinline__ void moba_kv_item(LAS unsigned char* lds, const Ptrs& P, int bh, int n, int part, bool split) {
;     ...
;     for (int qt = wid; qt < ntile; qt += 8) {
;         const bool valid = vn; const unsigned e = en;
;         const int t = (int)(e & 4095u), k = (int)(e >> 12);
;         bf16x8 qr[8];
; #pragma unroll
;         for (int ks = 0; ks < 8; ++ks) qr[ks] = qn[ks];
;         if (qt + 8 < ntile) { const int idx = beg + (qt + 8) * 32 + r32; vn = idx < end; en = list[vn ? idx : beg]; moba_load_q(qn, P, (size_t)(b * SEQ + (int)(en & 4095u)), h, hi); }
.LBB0_942:
	s_add_i32 s74, s74, 8
	s_cmp_ge_i32 s74, s77
	s_cselect_b64 s[44:45], -1, 0
	s_and_b64 vcc, exec, s[44:45]
	s_cbranch_vccnz .LBB0_944
	s_waitcnt lgkmcnt(0)
	v_lshl_add_u32 v1, s74, 5, v223
	v_mov_b32_e32 v2, s76
	v_cmp_gt_i32_e64 s[4:5], s75, v1
	v_mov_b32_e32 v217, v0
	s_nop 0
	v_cndmask_b32_e64 v2, v2, v1, s[4:5]
	v_ashrrev_i32_e32 v3, 31, v2
	v_lshl_add_u64 v[2:3], v[2:3], 2, s[34:35]
	s_cmp_lg_u32 s93, 0
	s_cbranch_scc1 .Lkve_have_kv0
	global_load_dword v227, v[2:3], off
	s_waitcnt vmcnt(0)
	s_branch .Lkve_go_kv0
.Lkve_have_kv0:
	v_mov_b32_e32 v227, v232
.Lkve_go_kv0:
	v_mov_b64_e32 v[2:3], s[26:27]
	s_and_b64 s[4:5], s[4:5], exec
	v_and_b32_e32 v1, 0xfff, v227
	v_or_b32_e32 v1, s70, v1
	v_mad_i64_i32 v[2:3], s[0:1], v1, s57, v[2:3]
	v_lshl_add_u64 v[2:3], v[2:3], 0, v[216:217]
	v_mad_i64_i32 v[4:5], s[0:1], v1, s57, v[212:213]
	v_add_co_u32_e32 v2, vcc, 0xef00000, v2
	s_andn2_b64 s[0:1], s[46:47], exec
	s_nop 0
	v_addc_co_u32_e32 v3, vcc, 0, v3, vcc
	global_load_dwordx4 v[144:147], v[4:5], off
	global_load_dwordx4 v[148:151], v[2:3], off offset:32
	global_load_dwordx4 v[152:155], v[2:3], off offset:64
	global_load_dwordx4 v[156:159], v[2:3], off offset:96
	global_load_dwordx4 v[160:163], v[2:3], off offset:128
	global_load_dwordx4 v[164:167], v[2:3], off offset:160
	global_load_dwordx4 v[168:171], v[2:3], off offset:192
	global_load_dwordx4 v[172:175], v[2:3], off offset:224
	s_add_i32 s92, s74, 8
	s_cmp_lt_i32 s92, s77
	s_cbranch_scc0 .Lkve_nopf_kv0
	v_lshl_add_u32 v234, s92, 5, v223
	v_mov_b32_e32 v236, s76
	v_cmp_gt_i32_e64 s[90:91], s75, v234
	s_nop 1
	v_cndmask_b32_e64 v234, v236, v234, s[90:91]
	v_ashrrev_i32_e32 v235, 31, v234
	v_lshl_add_u64 v[234:235], v[234:235], 2, s[34:35]
	global_load_dword v232, v[234:235], off
.Lkve_nopf_kv0:
	s_mov_b32 s93, 1
	s_or_b64 s[4:5], s[0:1], s[4:5]
